# grid barrier: waiting workgroups poll the top-level generation word directly instead of the per-XCD relay (on v44)
# speedup vs baseline: 1.0043x; 1.0041x over previous
; __device__ __forceinline__ unsigned xb_ld(unsigned* p)              { return __hip_atomic_load(p, __ATOMIC_RELAXED, __HIP_MEMORY_SCOPE_AGENT); }
; __device__ __forceinline__ unsigned xb_add(unsigned* p, unsigned v) { return __hip_atomic_fetch_add(p, v, __ATOMIC_RELAXED, __HIP_MEMORY_SCOPE_AGENT); }
; #define XB_SPIN(cond, bar) do { unsigned _sp = 0; while (cond) { __builtin_amdgcn_s_sleep(1); \
;     if ((++_sp & 255u) == 0u) { if (xb_ld(&(bar)[XB_TMO])) break; if (_sp > XB_SPIN_CAP) { atomicAdd(&(bar)[XB_TMO], 1u); break; } } } } while (0)
; __device__ __forceinline__ void xcd_barrier(unsigned* bar, volatile LAS unsigned* st, const int wid0) {
;     ...
;         const unsigned old = xb_add(&bar[XB_XSUB(x)], 1u);
;         const unsigned gen = old / nloc;
;         if (old + 1u == (gen + 1u) * nloc) {
;             __builtin_amdgcn_fence(__ATOMIC_RELEASE, "agent");
;             asm volatile("s_waitcnt vmcnt(0)" ::: "memory");
;             const unsigned og = xb_add(&bar[XB_TOP], 1u);
;             const unsigned tg = og / nx;
;             if (og + 1u == (tg + 1u) * nx) xb_add(&bar[XB_TOPGEN], 1u);
;             else XB_SPIN(xb_ld(&bar[XB_TOPGEN]) == tg, bar);
;             __builtin_amdgcn_fence(__ATOMIC_ACQUIRE, "agent");
;             xb_add(&bar[XB_XGEN(x)], 1u);
;             asm volatile("s_waitcnt vmcnt(0)" ::: "memory");
;         } else {
;             XB_SPIN(xb_ld(&bar[XB_XGEN(x)]) == gen, bar);
;             __builtin_amdgcn_fence(__ATOMIC_ACQUIRE, "agent");
;             asm volatile("s_waitcnt vmcnt(0)" ::: "memory");
;         }
.LBB0_438:
	s_or_b64 exec, exec, s[8:9]
	v_cvt_f32_u32_e32 v4, v2
	s_waitcnt vmcnt(0)
	v_readfirstlane_b32 s3, v3
	v_sub_u32_e32 v3, 0, v2
	v_rcp_iflag_f32_e32 v4, v4
	v_add_u32_e32 v5, s3, v1
	v_mul_f32_e32 v4, 0x4f7ffffe, v4
	v_cvt_u32_f32_e32 v4, v4
	v_mul_lo_u32 v1, v3, v4
	v_mul_hi_u32 v1, v4, v1
	v_add_u32_e32 v1, v4, v1
	v_mul_hi_u32 v1, v5, v1
	v_mul_lo_u32 v3, v1, v2
	v_sub_u32_e32 v3, v5, v3
	v_add_u32_e32 v4, 1, v1
	v_cmp_ge_u32_e32 vcc, v3, v2
	s_nop 1
	v_cndmask_b32_e32 v1, v1, v4, vcc
	v_sub_u32_e32 v4, v3, v2
	v_cndmask_b32_e32 v3, v3, v4, vcc
	v_add_u32_e32 v4, 1, v1
	v_cmp_ge_u32_e32 vcc, v3, v2
	v_add_u32_e32 v3, 1, v5
	s_nop 0
	v_cndmask_b32_e32 v1, v1, v4, vcc
	v_mul_lo_u32 v4, v2, v1
	v_add_u32_e32 v2, v4, v2
	v_cmp_ne_u32_e32 vcc, v3, v2
	s_and_saveexec_b64 s[6:7], vcc
	s_xor_b64 s[6:7], exec, s[6:7]
	s_cbranch_execz .LBB0_452
	s_waitcnt lgkmcnt(0)
	v_mov_b32_e32 v0, 0x2000
	s_add_u32 s12, s26, 0x7181100
	s_addc_u32 s13, s27, 0
	global_load_dword v0, v0, s[12:13] offset:1024 sc1
	s_add_u32 s12, s12, 0x2400
	s_addc_u32 s13, s13, 0
	s_waitcnt vmcnt(0)
	v_cmp_eq_u32_e32 vcc, v0, v1
	s_and_saveexec_b64 s[8:9], vcc
	s_cbranch_execz .LBB0_451
	s_add_u32 s10, s26, 0x7180200
	s_addc_u32 s11, s27, 0
	s_mov_b32 s3, 1
	s_mov_b64 s[14:15], 0
	v_mov_b32_e32 v0, 0
	s_branch .LBB0_442

; __device__ __forceinline__ unsigned xb_ld(unsigned* p)              { return __hip_atomic_load(p, __ATOMIC_RELAXED, __HIP_MEMORY_SCOPE_AGENT); }
; __device__ __forceinline__ unsigned xb_add(unsigned* p, unsigned v) { return __hip_atomic_fetch_add(p, v, __ATOMIC_RELAXED, __HIP_MEMORY_SCOPE_AGENT); }
; #define XB_SPIN(cond, bar) do { unsigned _sp = 0; while (cond) { __builtin_amdgcn_s_sleep(1); \
;     if ((++_sp & 255u) == 0u) { if (xb_ld(&(bar)[XB_TMO])) break; if (_sp > XB_SPIN_CAP) { atomicAdd(&(bar)[XB_TMO], 1u); break; } } } } while (0)
; __device__ __forceinline__ void xcd_barrier(unsigned* bar, volatile LAS unsigned* st, const int wid0) {
;     ...
;         const unsigned old = xb_add(&bar[XB_XSUB(x)], 1u);
;         const unsigned gen = old / nloc;
;         if (old + 1u == (gen + 1u) * nloc) {
;             __builtin_amdgcn_fence(__ATOMIC_RELEASE, "agent");
;             asm volatile("s_waitcnt vmcnt(0)" ::: "memory");
;             const unsigned og = xb_add(&bar[XB_TOP], 1u);
;             const unsigned tg = og / nx;
;             if (og + 1u == (tg + 1u) * nx) xb_add(&bar[XB_TOPGEN], 1u);
;             else XB_SPIN(xb_ld(&bar[XB_TOPGEN]) == tg, bar);
;             __builtin_amdgcn_fence(__ATOMIC_ACQUIRE, "agent");
;             xb_add(&bar[XB_XGEN(x)], 1u);
;             asm volatile("s_waitcnt vmcnt(0)" ::: "memory");
;         } else {
;             XB_SPIN(xb_ld(&bar[XB_XGEN(x)]) == gen, bar);
;             __builtin_amdgcn_fence(__ATOMIC_ACQUIRE, "agent");
;             asm volatile("s_waitcnt vmcnt(0)" ::: "memory");
;         }
.LBB0_847:
	s_or_b64 exec, exec, s[12:13]
	v_cvt_f32_u32_e32 v4, v2
	s_waitcnt vmcnt(0)
	v_readfirstlane_b32 s2, v3
	v_sub_u32_e32 v3, 0, v2
	v_rcp_iflag_f32_e32 v4, v4
	v_add_u32_e32 v5, s2, v1
	v_mul_f32_e32 v4, 0x4f7ffffe, v4
	v_cvt_u32_f32_e32 v4, v4
	v_mul_lo_u32 v1, v3, v4
	v_mul_hi_u32 v1, v4, v1
	v_add_u32_e32 v1, v4, v1
	v_mul_hi_u32 v1, v5, v1
	v_mul_lo_u32 v3, v1, v2
	v_sub_u32_e32 v3, v5, v3
	v_add_u32_e32 v4, 1, v1
	v_cmp_ge_u32_e32 vcc, v3, v2
	s_nop 1
	v_cndmask_b32_e32 v1, v1, v4, vcc
	v_sub_u32_e32 v4, v3, v2
	v_cndmask_b32_e32 v3, v3, v4, vcc
	v_add_u32_e32 v4, 1, v1
	v_cmp_ge_u32_e32 vcc, v3, v2
	v_add_u32_e32 v3, 1, v5
	s_nop 0
	v_cndmask_b32_e32 v1, v1, v4, vcc
	v_mul_lo_u32 v4, v2, v1
	v_add_u32_e32 v2, v4, v2
	v_cmp_ne_u32_e32 vcc, v3, v2
	s_and_saveexec_b64 s[2:3], vcc
	s_xor_b64 s[8:9], exec, s[2:3]
	s_cbranch_execz .LBB0_861
	s_waitcnt lgkmcnt(0)
	v_mov_b32_e32 v0, 0x2000
	s_add_u32 s30, s26, 0x7181100
	s_addc_u32 s31, s27, 0
	global_load_dword v0, v0, s[30:31] offset:1024 sc1
	s_add_u32 s30, s30, 0x2400
	s_addc_u32 s31, s31, 0
	s_waitcnt vmcnt(0)
	v_cmp_eq_u32_e32 vcc, v0, v1
	s_and_saveexec_b64 s[12:13], vcc
	s_cbranch_execz .LBB0_860
	s_mov_b32 s2, 1
	s_mov_b64 s[34:35], 0
	s_branch .LBB0_851

; __device__ __forceinline__ unsigned xb_ld(unsigned* p)              { return __hip_atomic_load(p, __ATOMIC_RELAXED, __HIP_MEMORY_SCOPE_AGENT); }
; __device__ __forceinline__ unsigned xb_add(unsigned* p, unsigned v) { return __hip_atomic_fetch_add(p, v, __ATOMIC_RELAXED, __HIP_MEMORY_SCOPE_AGENT); }
; #define XB_SPIN(cond, bar) do { unsigned _sp = 0; while (cond) { __builtin_amdgcn_s_sleep(1); \
;     if ((++_sp & 255u) == 0u) { if (xb_ld(&(bar)[XB_TMO])) break; if (_sp > XB_SPIN_CAP) { atomicAdd(&(bar)[XB_TMO], 1u); break; } } } } while (0)
; __device__ __forceinline__ void xcd_barrier(unsigned* bar, volatile LAS unsigned* st, const int wid0) {
;     ...
;         const unsigned old = xb_add(&bar[XB_XSUB(x)], 1u);
;         const unsigned gen = old / nloc;
;         if (old + 1u == (gen + 1u) * nloc) {
;             __builtin_amdgcn_fence(__ATOMIC_RELEASE, "agent");
;             asm volatile("s_waitcnt vmcnt(0)" ::: "memory");
;             const unsigned og = xb_add(&bar[XB_TOP], 1u);
;             const unsigned tg = og / nx;
;             if (og + 1u == (tg + 1u) * nx) xb_add(&bar[XB_TOPGEN], 1u);
;             else XB_SPIN(xb_ld(&bar[XB_TOPGEN]) == tg, bar);
;             __builtin_amdgcn_fence(__ATOMIC_ACQUIRE, "agent");
;             xb_add(&bar[XB_XGEN(x)], 1u);
;             asm volatile("s_waitcnt vmcnt(0)" ::: "memory");
;         } else {
;             XB_SPIN(xb_ld(&bar[XB_XGEN(x)]) == gen, bar);
;             __builtin_amdgcn_fence(__ATOMIC_ACQUIRE, "agent");
;             asm volatile("s_waitcnt vmcnt(0)" ::: "memory");
;         }
.LBB0_997:
	s_or_b64 exec, exec, s[10:11]
	v_cvt_f32_u32_e32 v4, v2
	s_waitcnt vmcnt(0)
	v_readfirstlane_b32 s2, v3
	v_sub_u32_e32 v3, 0, v2
	v_rcp_iflag_f32_e32 v4, v4
	v_add_u32_e32 v5, s2, v1
	v_mul_f32_e32 v4, 0x4f7ffffe, v4
	v_cvt_u32_f32_e32 v4, v4
	v_mul_lo_u32 v1, v3, v4
	v_mul_hi_u32 v1, v4, v1
	v_add_u32_e32 v1, v4, v1
	v_mul_hi_u32 v1, v5, v1
	v_mul_lo_u32 v3, v1, v2
	v_sub_u32_e32 v3, v5, v3
	v_add_u32_e32 v4, 1, v1
	v_cmp_ge_u32_e32 vcc, v3, v2
	s_nop 1
	v_cndmask_b32_e32 v1, v1, v4, vcc
	v_sub_u32_e32 v4, v3, v2
	v_cndmask_b32_e32 v3, v3, v4, vcc
	v_add_u32_e32 v4, 1, v1
	v_cmp_ge_u32_e32 vcc, v3, v2
	v_add_u32_e32 v3, 1, v5
	s_nop 0
	v_cndmask_b32_e32 v1, v1, v4, vcc
	v_mul_lo_u32 v4, v2, v1
	v_add_u32_e32 v2, v4, v2
	v_cmp_ne_u32_e32 vcc, v3, v2
	s_and_saveexec_b64 s[2:3], vcc
	s_xor_b64 s[8:9], exec, s[2:3]
	s_cbranch_execz .LBB0_1011
	s_waitcnt lgkmcnt(0)
	v_mov_b32_e32 v0, 0x2000
	s_add_u32 s30, s26, 0x7181100
	s_addc_u32 s31, s27, 0
	global_load_dword v0, v0, s[30:31] offset:1024 sc1
	s_add_u32 s30, s30, 0x2400
	s_addc_u32 s31, s31, 0
	s_waitcnt vmcnt(0)
	v_cmp_eq_u32_e32 vcc, v0, v1
	s_and_saveexec_b64 s[10:11], vcc
	s_cbranch_execz .LBB0_1010
	s_mov_b32 s2, 1
	s_mov_b64 s[34:35], 0
	s_branch .LBB0_1001

; __device__ __forceinline__ unsigned xb_ld(unsigned* p)              { return __hip_atomic_load(p, __ATOMIC_RELAXED, __HIP_MEMORY_SCOPE_AGENT); }
; __device__ __forceinline__ unsigned xb_add(unsigned* p, unsigned v) { return __hip_atomic_fetch_add(p, v, __ATOMIC_RELAXED, __HIP_MEMORY_SCOPE_AGENT); }
; #define XB_SPIN(cond, bar) do { unsigned _sp = 0; while (cond) { __builtin_amdgcn_s_sleep(1); \
;     if ((++_sp & 255u) == 0u) { if (xb_ld(&(bar)[XB_TMO])) break; if (_sp > XB_SPIN_CAP) { atomicAdd(&(bar)[XB_TMO], 1u); break; } } } } while (0)
; __device__ __forceinline__ void xcd_barrier(unsigned* bar, volatile LAS unsigned* st, const int wid0) {
;     ...
;         const unsigned old = xb_add(&bar[XB_XSUB(x)], 1u);
;         const unsigned gen = old / nloc;
;         if (old + 1u == (gen + 1u) * nloc) {
;             __builtin_amdgcn_fence(__ATOMIC_RELEASE, "agent");
;             asm volatile("s_waitcnt vmcnt(0)" ::: "memory");
;             const unsigned og = xb_add(&bar[XB_TOP], 1u);
;             const unsigned tg = og / nx;
;             if (og + 1u == (tg + 1u) * nx) xb_add(&bar[XB_TOPGEN], 1u);
;             else XB_SPIN(xb_ld(&bar[XB_TOPGEN]) == tg, bar);
;             __builtin_amdgcn_fence(__ATOMIC_ACQUIRE, "agent");
;             xb_add(&bar[XB_XGEN(x)], 1u);
;             asm volatile("s_waitcnt vmcnt(0)" ::: "memory");
;         } else {
;             XB_SPIN(xb_ld(&bar[XB_XGEN(x)]) == gen, bar);
;             __builtin_amdgcn_fence(__ATOMIC_ACQUIRE, "agent");
;             asm volatile("s_waitcnt vmcnt(0)" ::: "memory");
;         }
.LBB0_1096:
	s_or_b64 exec, exec, s[30:31]
	v_cvt_f32_u32_e32 v4, v2
	s_waitcnt vmcnt(0)
	v_readfirstlane_b32 s2, v3
	v_sub_u32_e32 v3, 0, v2
	v_rcp_iflag_f32_e32 v4, v4
	v_add_u32_e32 v5, s2, v1
	v_mul_f32_e32 v4, 0x4f7ffffe, v4
	v_cvt_u32_f32_e32 v4, v4
	v_mul_lo_u32 v1, v3, v4
	v_mul_hi_u32 v1, v4, v1
	v_add_u32_e32 v1, v4, v1
	v_mul_hi_u32 v1, v5, v1
	v_mul_lo_u32 v3, v1, v2
	v_sub_u32_e32 v3, v5, v3
	v_add_u32_e32 v4, 1, v1
	v_cmp_ge_u32_e32 vcc, v3, v2
	s_nop 1
	v_cndmask_b32_e32 v1, v1, v4, vcc
	v_sub_u32_e32 v4, v3, v2
	v_cndmask_b32_e32 v3, v3, v4, vcc
	v_add_u32_e32 v4, 1, v1
	v_cmp_ge_u32_e32 vcc, v3, v2
	v_add_u32_e32 v3, 1, v5
	s_nop 0
	v_cndmask_b32_e32 v1, v1, v4, vcc
	v_mul_lo_u32 v4, v2, v1
	v_add_u32_e32 v2, v4, v2
	v_cmp_ne_u32_e32 vcc, v3, v2
	s_and_saveexec_b64 s[2:3], vcc
	s_xor_b64 s[10:11], exec, s[2:3]
	s_cbranch_execz .LBB0_1110
	s_waitcnt lgkmcnt(0)
	v_mov_b32_e32 v0, 0x2000
	s_add_u32 s34, s26, 0x7181100
	s_addc_u32 s35, s27, 0
	global_load_dword v0, v0, s[34:35] offset:1024 sc1
	s_add_u32 s34, s34, 0x2400
	s_addc_u32 s35, s35, 0
	s_waitcnt vmcnt(0)
	v_cmp_eq_u32_e32 vcc, v0, v1
	s_and_saveexec_b64 s[30:31], vcc
	s_cbranch_execz .LBB0_1109
	s_mov_b32 s2, 1
	s_mov_b64 s[36:37], 0
	s_branch .LBB0_1100
